# GEMM-up epilogue row loop: 32-bit row-index compares, packed exp-argument multiplies, stale s_nop removed
# baseline (speedup 1.0000x reference)
; #define UFOR(v, n) _Pragma("unroll") for (int v = 0; v < (n); ++v)
; #define LDS_BARRIER() do { asm volatile("s_waitcnt lgkmcnt(0)" ::: "memory"); __builtin_amdgcn_s_barrier(); asm volatile("" ::: "memory"); } while (0)
; __device__ __forceinline__ unsigned pk2(float a, float b) { return (unsigned)f2bf(a) | ((unsigned)f2bf(b) << 16); }
; __device__ __forceinline__ float lo2f(unsigned u) { return __uint_as_float(u << 16); }
; __device__ __forceinline__ float hi2f(unsigned u) { return __uint_as_float(u & 0xffff0000u); }
; template <int EPI, int K, int KL> ...
;     ...
;     u16* U = (u16*)smem;
;     LDS_BARRIER();
;     UFOR(ai, 2) UFOR(bj, 2) UFOR(m, 4) {
;       const f32x4 a = acc[ai][bj][m][0], b = acc[ai][bj][m][1];
;       uint4 pk; pk.x = pk2(a[0], a[1]); pk.y = pk2(a[2], a[3]); pk.z = pk2(b[0], b[1]); pk.w = pk2(b[2], b[3]);
;       *(uint4*)(U + (ai * HALF + wr * 64 + m * 16 + fr) * 256 + bj * 128 + wc * 32 + fq * 8) = pk;
;     }
;     LDS_BARRIER();
;     {
;       const int c4 = (tid_ & 31) * 4, rb = tid_ >> 5;
;       const int gc = pn * 128 + c4;
;       float wg[4][3], wv[4][3];
;       UFOR(q, 4) UFOR(x, 3) { wg[q][x] = e.cw[(size_t)(gc + q) * 3 + x]; wv[q][x] = e.cw[(size_t)(DFF + gc + q) * 3 + x]; }
;       float pg[4], cgv[4], ng[4], pvv[4], cv[4], nv[4];
;       const int lr0 = rb * 16;
;       {
;         const int lrp = lr0 > 0 ? lr0 - 1 : 0;
;         const uint2 a = *(const uint2*)(U + lrp * 256 + c4), b = *(const uint2*)(U + lrp * 256 + 128 + c4);
;         pg[0] = lo2f(a.x); pg[1] = hi2f(a.x); pg[2] = lo2f(a.y); pg[3] = hi2f(a.y);
;         pvv[0] = lo2f(b.x); pvv[1] = hi2f(b.x); pvv[2] = lo2f(b.y); pvv[3] = hi2f(b.y);
;         const uint2 c = *(const uint2*)(U + lr0 * 256 + c4), d = *(const uint2*)(U + lr0 * 256 + 128 + c4);
;         cgv[0] = lo2f(c.x); cgv[1] = hi2f(c.x); cgv[2] = lo2f(c.y); cgv[3] = hi2f(c.y);
;         cv[0] = lo2f(d.x); cv[1] = hi2f(d.x); cv[2] = lo2f(d.y); cv[3] = hi2f(d.y);
;       }
.LBB0_1110:
	s_or_b64 exec, exec, s[40:41]
	v_lshlrev_b32_e32 v128, 6, v155
	v_add3_u32 v128, 0, v128, v156
	v_lshlrev_b32_e32 v129, 15, v153
	v_lshlrev_b32_e32 v130, 9, v154
	v_add3_u32 v128, v128, v129, v130
	v_cvt_pk_bf16_f32 v124, v124, v125
	v_cvt_pk_bf16_f32 v125, v126, v127
	v_cvt_pk_bf16_f32 v126, v120, v121
	v_cvt_pk_bf16_f32 v116, v116, v117
	v_cvt_pk_bf16_f32 v117, v118, v119
	v_cvt_pk_bf16_f32 v118, v112, v113
	v_cvt_pk_bf16_f32 v108, v108, v109
	v_cvt_pk_bf16_f32 v109, v110, v111
	v_cvt_pk_bf16_f32 v110, v104, v105
	v_cvt_pk_bf16_f32 v100, v100, v101
	v_cvt_pk_bf16_f32 v101, v102, v103
	v_cvt_pk_bf16_f32 v102, v96, v97
	v_cvt_pk_bf16_f32 v92, v92, v93
	v_cvt_pk_bf16_f32 v93, v94, v95
	v_cvt_pk_bf16_f32 v94, v88, v89
	v_cvt_pk_bf16_f32 v84, v84, v85
	v_cvt_pk_bf16_f32 v85, v86, v87
	v_cvt_pk_bf16_f32 v86, v80, v81
	v_cvt_pk_bf16_f32 v76, v76, v77
	v_cvt_pk_bf16_f32 v77, v78, v79
	v_cvt_pk_bf16_f32 v78, v72, v73
	v_cvt_pk_bf16_f32 v68, v68, v69
	v_cvt_pk_bf16_f32 v69, v70, v71
	v_cvt_pk_bf16_f32 v70, v64, v65
	v_cvt_pk_bf16_f32 v71, v66, v67
	v_cvt_pk_bf16_f32 v60, v60, v61
	v_cvt_pk_bf16_f32 v61, v62, v63
	v_cvt_pk_bf16_f32 v62, v56, v57
	v_cvt_pk_bf16_f32 v63, v58, v59
	v_cvt_pk_bf16_f32 v52, v52, v53
	v_cvt_pk_bf16_f32 v53, v54, v55
	v_cvt_pk_bf16_f32 v54, v48, v49
	v_cvt_pk_bf16_f32 v55, v50, v51
	v_cvt_pk_bf16_f32 v44, v44, v45
	v_cvt_pk_bf16_f32 v45, v46, v47
	v_cvt_pk_bf16_f32 v46, v40, v41
	v_cvt_pk_bf16_f32 v47, v42, v43
	v_cvt_pk_bf16_f32 v36, v36, v37
	v_cvt_pk_bf16_f32 v37, v38, v39
	v_cvt_pk_bf16_f32 v38, v32, v33
	v_cvt_pk_bf16_f32 v39, v34, v35
	v_cvt_pk_bf16_f32 v28, v28, v29
	v_cvt_pk_bf16_f32 v29, v30, v31
	v_cvt_pk_bf16_f32 v30, v24, v25
	v_cvt_pk_bf16_f32 v31, v26, v27
	v_cvt_pk_bf16_f32 v20, v20, v21
	v_cvt_pk_bf16_f32 v21, v22, v23
	v_cvt_pk_bf16_f32 v22, v16, v17
	v_cvt_pk_bf16_f32 v23, v18, v19
	v_cvt_pk_bf16_f32 v12, v12, v13
	v_cvt_pk_bf16_f32 v13, v14, v15
	v_cvt_pk_bf16_f32 v14, v8, v9
	v_cvt_pk_bf16_f32 v15, v10, v11
	v_cvt_pk_bf16_f32 v4, v4, v5
	v_cvt_pk_bf16_f32 v5, v6, v7
	v_cvt_pk_bf16_f32 v127, v122, v123
	v_cvt_pk_bf16_f32 v119, v114, v115
	v_cvt_pk_bf16_f32 v111, v106, v107
	v_cvt_pk_bf16_f32 v103, v98, v99
	v_cvt_pk_bf16_f32 v95, v90, v91
	v_cvt_pk_bf16_f32 v87, v82, v83
	v_cvt_pk_bf16_f32 v79, v74, v75
	v_cvt_pk_bf16_f32 v7, v2, v3
	v_cvt_pk_bf16_f32 v6, v0, v1
	v_add_u32_e32 v16, 0x14100, v128
	s_waitcnt lgkmcnt(0)
	s_barrier
	v_add_u32_e32 v32, 0x10100, v128
	ds_write_b128 v16, v[12:15]
	v_and_b32_e32 v16, 0x7c, v132
	v_add_u32_e32 v64, 0x10000, v128
	v_add_u32_e32 v56, 0x12000, v128
	v_add_u32_e32 v48, 0x14000, v128
	v_add_u32_e32 v40, 0x16000, v128
	ds_write_b128 v32, v[28:31]
	v_add_u32_e32 v24, 0x12100, v128
	v_add_u32_e32 v8, 0x16100, v128
	v_lshl_or_b32 v32, s51, 7, v16
	ds_write_b128 v128, v[124:127]
	ds_write_b128 v128, v[116:119] offset:8192
	ds_write_b128 v128, v[108:111] offset:16384
	ds_write_b128 v128, v[100:103] offset:24576
	ds_write_b128 v128, v[92:95] offset:256
	ds_write_b128 v128, v[84:87] offset:8448
	ds_write_b128 v128, v[76:79] offset:16640
	ds_write_b128 v128, v[68:71] offset:24832
	ds_write_b128 v64, v[60:63]
	ds_write_b128 v56, v[52:55]
	ds_write_b128 v48, v[44:47]
	ds_write_b128 v40, v[36:39]
	ds_write_b128 v24, v[20:23]
	ds_write_b128 v8, v[4:7]
	v_add_u32_e32 v0, 0x1600, v32
	s_waitcnt lgkmcnt(0)
	s_barrier
	v_mad_i64_i32 v[4:5], s[40:41], v0, 12, s[46:47]
	v_mad_i64_i32 v[12:13], s[40:41], v32, 12, s[46:47]
	global_load_dwordx4 v[24:27], v[4:5], off offset:16
	global_load_dwordx4 v[0:3], v[4:5], off offset:32
	s_nop 0
	global_load_dwordx4 v[4:7], v[4:5], off
	s_nop 0
	global_load_dwordx4 v[8:11], v[12:13], off offset:16
	global_load_dwordx4 v[28:31], v[12:13], off offset:32
	s_nop 0
	global_load_dwordx4 v[12:15], v[12:13], off
	v_ashrrev_i32_e32 v34, 1, v152
	v_and_b32_e32 v132, -16, v34
	v_mov_b32_e32 v17, 0xffffff00
	v_lshl_add_u32 v17, v132, 8, v17
	v_cmp_lt_i32_e32 vcc, 15, v34
	v_lshl_add_u32 v64, v16, 1, 0
	s_ashr_i32 s51, s50, 31
	v_cndmask_b32_e32 v17, 0, v17, vcc
	v_lshl_add_u32 v16, v17, 1, v64
	ds_read2_b64 v[16:19], v16 offset1:32
	s_ashr_i32 s53, s52, 31
	s_add_u32 s56, s52, -1
	s_addc_u32 s57, s53, -1
	s_add_i32 s61, s52, -1
	s_waitcnt lgkmcnt(0)
	v_and_b32_e32 v56, 0xffff0000, v16
	v_lshlrev_b32_e32 v58, 16, v16
	v_lshl_add_u32 v16, v132, 9, v64
	ds_read2_b64 v[20:23], v16 offset1:32
	s_ashr_i32 s62, s61, 31
	v_ashrrev_i32_e32 v33, 31, v32
	v_cmp_lt_i32_e64 s[40:41], -1, v34
	s_sub_u32 s58, s50, s42
	v_ashrrev_i32_e32 v35, 31, v132
	v_mov_b32_e32 v34, v132
	s_waitcnt lgkmcnt(0)
	v_lshlrev_b32_e32 v47, 16, v21
	v_lshlrev_b32_e32 v46, 16, v20
	v_and_b32_e32 v45, 0xffff0000, v21
	v_and_b32_e32 v44, 0xffff0000, v20
	v_lshlrev_b32_e32 v50, 16, v22
	v_lshlrev_b32_e32 v51, 16, v23
	v_and_b32_e32 v49, 0xffff0000, v23
	v_and_b32_e32 v48, 0xffff0000, v22
	s_subb_u32 s59, s51, s43
	s_movk_i32 s63, 0x2c00
	v_lshlrev_b32_e32 v63, 16, v19
	v_lshlrev_b32_e32 v62, 16, v18
	v_and_b32_e32 v61, 0xffff0000, v19
	v_and_b32_e32 v60, 0xffff0000, v18
	v_and_b32_e32 v57, 0xffff0000, v17
	v_lshlrev_b32_e32 v59, 16, v17
	v_mov_b32_e32 v248, 0x3a27c5ac
	s_waitcnt vmcnt(0)
	v_mov_b32_e32 v16, v24
	v_mov_b32_e32 v20, v9
	v_mov_b32_e32 v21, v31
	v_mov_b32_e32 v9, v30
	v_mov_b32_e32 v22, v15
	v_mov_b32_e32 v23, v29
	v_mov_b32_e32 v15, v28
	v_lshl_add_u64 v[28:29], s[42:43], 0, v[34:35]
	v_lshlrev_b64 v[30:31], 1, v[32:33]
	v_mov_b32_e32 v18, v7
	v_mov_b32_e32 v19, v1
	v_mov_b32_e32 v7, v0
	v_mov_b32_e32 v0, v13
	v_mov_b32_e32 v1, v11
	v_mov_b32_e32 v13, v10
	v_mov_b32_e32 v11, s59
	v_sub_co_u32_e32 v10, vcc, s58, v132
	v_mad_u64_u32 v[30:31], s[58:59], v28, s63, v[30:31]
	v_mov_b32_e32 v32, v31
	s_sub_u32 s42, s61, s42
	v_subb_co_u32_e32 v11, vcc, v11, v35, vcc
	v_mad_u64_u32 v[32:33], s[58:59], v29, s63, v[32:33]
	s_subb_u32 s43, s62, s43
	v_mov_b32_e32 v31, v32
	v_readlane_b32 s58, v254, 38
	v_mov_b32_e32 v33, s43
	v_sub_co_u32_e32 v32, vcc, s42, v132
	v_readlane_b32 s59, v254, 39
	s_nop 0
	v_subb_co_u32_e32 v33, vcc, v33, v35, vcc
	v_mov_b32_e32 v17, v2
	v_mov_b32_e32 v2, v25
	v_mov_b32_e32 v24, v5
	v_mov_b32_e32 v25, v27
	v_mov_b32_e32 v5, v26
	v_lshl_add_u64 v[26:27], v[10:11], 0, -1
	v_lshl_add_u64 v[30:31], s[58:59], 0, v[30:31]
	v_lshl_add_u64 v[34:35], v[32:33], 0, -1
	s_mov_b64 s[58:59], 0
	v_mov_b32_e32 v90, 0xbfb8aa3b
	s_branch .LBB0_1112

; #define UFOR(v, n) _Pragma("unroll") for (int v = 0; v < (n); ++v)
; __device__ __forceinline__ unsigned pk2(float a, float b) { return (unsigned)f2bf(a) | ((unsigned)f2bf(b) << 16); }
; __device__ __forceinline__ float lo2f(unsigned u) { return __uint_as_float(u << 16); }
; __device__ __forceinline__ float hi2f(unsigned u) { return __uint_as_float(u & 0xffff0000u); }
; __device__ __forceinline__ float siluf_(float x) { return x / (1.f + __expf(-x)); }
; template <int EPI, int K, int KL> ...
;     ...
;       for (int q = 0; q < 16; ++q) {
;         const int lr = lr0 + q;
;         const int lrn = lr < 255 ? lr + 1 : 255;
;         const uint2 a = *(const uint2*)(U + lrn * 256 + c4), b = *(const uint2*)(U + lrn * 256 + 128 + c4);
;         ng[0] = lo2f(a.x); ng[1] = hi2f(a.x); ng[2] = lo2f(a.y); ng[3] = hi2f(a.y);
;         nv[0] = lo2f(b.x); nv[1] = hi2f(b.x); nv[2] = lo2f(b.y); nv[3] = hi2f(b.y);
;         const long gr = brow + lr;
;         const bool valid = (gr >= seq0) && (gr < seq1) && (lr >= 1 || gr == seq0) && (lr <= 254 || gr == seq1 - 1);
;         if (valid) {
;           const float mp = (gr - 1 >= seq0) ? 1.f : 0.f, mn = (gr + 1 < seq1) ? 1.f : 0.f;
;           float o[4];
;           UFOR(x, 4) {
;             const float g = wg[x][0] * pg[x] * mp + wg[x][1] * cgv[x] + wg[x][2] * ng[x] * mn;
;             const float v = wv[x][0] * pvv[x] * mp + wv[x][1] * cv[x] + wv[x][2] * nv[x] * mn;
;             o[x] = siluf_(g) * v;
;           }
;           uint2 pk; pk.x = pk2(o[0], o[1]); pk.y = pk2(o[2], o[3]);
;           *(uint2*)(e.h2 + (size_t)gr * DFF + gc) = pk;
;         }
.LBB0_1112:
	v_lshl_add_u64 v[52:53], v[132:133], 0, s[58:59]
	v_min_i32_e32 v36, 0xfe, v52
	v_lshl_add_u32 v36, v36, 9, v64
	v_lshl_add_u64 v[54:55], v[28:29], 0, s[58:59]
	ds_read2_b64 v[40:43], v36 offset0:64 offset1:96
	v_cmp_le_i32_e32 vcc, s50, v54
	v_cmp_gt_i32_e64 s[42:43], s52, v54
	s_and_b64 s[62:63], vcc, s[42:43]
	v_cmp_lt_i32_e32 vcc, 0, v52
	v_cmp_eq_u32_e64 s[42:43], s58, v10
	s_or_b64 s[42:43], vcc, s[42:43]
	s_and_b64 s[62:63], s[62:63], s[42:43]
	v_cmp_gt_i32_e32 vcc, s27, v52
	v_cmp_eq_u32_e64 s[42:43], s58, v32
	s_or_b64 s[42:43], vcc, s[42:43]
	s_waitcnt lgkmcnt(0)
	v_lshlrev_b32_e32 v36, 16, v40
	v_lshlrev_b32_e32 v37, 16, v41
	v_and_b32_e32 v39, 0xffff0000, v41
	v_and_b32_e32 v38, 0xffff0000, v40
	v_lshlrev_b32_e32 v40, 16, v42
	v_lshlrev_b32_e32 v41, 16, v43
	v_and_b32_e32 v43, 0xffff0000, v43
	v_and_b32_e32 v42, 0xffff0000, v42
	s_and_b64 s[62:63], s[62:63], s[42:43]
	s_and_saveexec_b64 s[42:43], s[62:63]
	s_cbranch_execz .LBB0_1114
	v_cmp_lt_i32_e32 vcc, s50, v54
	v_pk_mul_f32 v[58:59], v[12:13], v[58:59]
	v_pk_mul_f32 v[56:57], v[22:23], v[56:57]
	v_cndmask_b32_e64 v66, 0, 1.0, vcc
	v_cmp_gt_i32_e32 vcc, s56, v54
	v_pk_mul_f32 v[58:59], v[58:59], v[66:67] op_sel_hi:[1,0]
	v_pk_mul_f32 v[70:71], v[14:15], v[36:37]
	v_cndmask_b32_e64 v68, 0, 1.0, vcc
	v_pk_fma_f32 v[58:59], v[0:1], v[46:47], v[58:59]
	v_pk_mul_f32 v[56:57], v[56:57], v[66:67] op_sel_hi:[1,0]
	v_pk_mul_f32 v[74:75], v[20:21], v[38:39]
	v_pk_fma_f32 v[58:59], v[70:71], v[68:69], v[58:59] op_sel_hi:[1,0,1]
	v_pk_fma_f32 v[56:57], v[8:9], v[44:45], v[56:57]
	v_pk_mul_f32 v[92:93], v[58:59], v[90:91] op_sel_hi:[1,0]
	v_pk_fma_f32 v[56:57], v[74:75], v[68:69], v[56:57] op_sel_hi:[1,0,1]
	v_exp_f32_e32 v70, v92
	v_pk_mul_f32 v[94:95], v[56:57], v[90:91] op_sel_hi:[1,0]
	v_exp_f32_e32 v74, v94
	v_exp_f32_e32 v71, v93
	v_pk_mul_f32 v[62:63], v[4:5], v[62:63]
	v_pk_mul_f32 v[72:73], v[6:7], v[40:41]
	v_pk_mul_f32 v[62:63], v[62:63], v[66:67] op_sel_hi:[1,0]
	v_pk_add_f32 v[70:71], v[70:71], 1.0 op_sel_hi:[1,0]
	v_pk_fma_f32 v[62:63], v[24:25], v[50:51], v[62:63]
	v_pk_fma_f32 v[62:63], v[68:69], v[72:73], v[62:63] op_sel_hi:[0,1,1]
	v_pk_mul_f32 v[60:61], v[18:19], v[60:61]
	v_pk_mul_f32 v[76:77], v[2:3], v[42:43]
	v_div_scale_f32 v80, vcc, v70, v70, v58
	v_div_scale_f32 v81, vcc, v71, v71, v59
	v_rcp_f32_e32 v82, v80
	v_rcp_f32_e32 v83, v81
	v_div_scale_f32 v86, s[62:63], v58, v70, v58
	v_div_scale_f32 v87, vcc, v59, v71, v59
	v_pk_fma_f32 v[84:85], v[80:81], v[82:83], 1.0 op_sel_hi:[1,1,0] neg_lo:[1,0,0] neg_hi:[1,0,0]
	v_pk_fma_f32 v[82:83], v[84:85], v[82:83], v[82:83]
	v_pk_mul_f32 v[88:89], v[86:87], v[82:83]
	v_pk_fma_f32 v[84:85], v[80:81], v[88:89], v[86:87] neg_lo:[1,0,0] neg_hi:[1,0,0]
	v_pk_fma_f32 v[88:89], v[84:85], v[82:83], v[88:89]
	v_pk_fma_f32 v[84:85], v[80:81], v[88:89], v[86:87] neg_lo:[1,0,0] neg_hi:[1,0,0]
	v_div_fmas_f32 v85, v85, v83, v89
	s_mov_b64 vcc, s[62:63]
	v_div_fmas_f32 v84, v84, v82, v88
	v_div_fixup_f32 v59, v85, v71, v59
	v_div_fixup_f32 v58, v84, v70, v58
	v_exp_f32_e32 v75, v95
	v_pk_mul_f32 v[58:59], v[62:63], v[58:59]
	v_pk_mul_f32 v[60:61], v[60:61], v[66:67] op_sel_hi:[1,0]
	v_pk_add_f32 v[62:63], v[74:75], 1.0 op_sel_hi:[1,0]
	v_pk_fma_f32 v[60:61], v[16:17], v[48:49], v[60:61]
	v_pk_fma_f32 v[60:61], v[68:69], v[76:77], v[60:61] op_sel_hi:[0,1,1]
	v_div_scale_f32 v80, vcc, v62, v62, v56
	v_div_scale_f32 v81, vcc, v63, v63, v57
	v_rcp_f32_e32 v82, v80
	v_rcp_f32_e32 v83, v81
	v_div_scale_f32 v86, s[62:63], v56, v62, v56
	v_div_scale_f32 v87, vcc, v57, v63, v57
	v_pk_fma_f32 v[84:85], v[80:81], v[82:83], 1.0 op_sel_hi:[1,1,0] neg_lo:[1,0,0] neg_hi:[1,0,0]
	v_pk_fma_f32 v[82:83], v[84:85], v[82:83], v[82:83]
	v_pk_mul_f32 v[88:89], v[86:87], v[82:83]
	v_pk_fma_f32 v[84:85], v[80:81], v[88:89], v[86:87] neg_lo:[1,0,0] neg_hi:[1,0,0]
	v_pk_fma_f32 v[88:89], v[84:85], v[82:83], v[88:89]
	v_pk_fma_f32 v[84:85], v[80:81], v[88:89], v[86:87] neg_lo:[1,0,0] neg_hi:[1,0,0]
	v_div_fmas_f32 v85, v85, v83, v89
	s_mov_b64 vcc, s[62:63]
	v_div_fmas_f32 v84, v84, v82, v88
	v_div_fixup_f32 v57, v85, v63, v57
	v_div_fixup_f32 v56, v84, v62, v56
	v_pk_mul_f32 v[56:57], v[60:61], v[56:57]
	v_cvt_pk_bf16_f32 v56, v58, v56
	v_cvt_pk_bf16_f32 v57, v59, v57
	v_add_co_u32_e32 v58, vcc, 0xffffe000, v30
	s_nop 0
	v_addc_co_u32_e32 v59, vcc, -1, v31, vcc
	global_store_dwordx2 v[58:59], v[56:57], off offset:-3072
; #define UFOR(v, n) _Pragma("unroll") for (int v = 0; v < (n); ++v)
; __device__ __forceinline__ unsigned pk2(float a, float b) { return (unsigned)f2bf(a) | ((unsigned)f2bf(b) << 16); }
; __device__ __forceinline__ float lo2f(unsigned u) { return __uint_as_float(u << 16); }
; __device__ __forceinline__ float hi2f(unsigned u) { return __uint_as_float(u & 0xffff0000u); }
; __device__ __forceinline__ float siluf_(float x) { return x / (1.f + __expf(-x)); }
; template <int EPI, int K, int KL> ...
;     ...
;       for (int q = 0; q < 16; ++q) {
;         const int lr = lr0 + q;
;         const int lrn = lr < 255 ? lr + 1 : 255;
;         const uint2 a = *(const uint2*)(U + lrn * 256 + c4), b = *(const uint2*)(U + lrn * 256 + 128 + c4);
;         ng[0] = lo2f(a.x); ng[1] = hi2f(a.x); ng[2] = lo2f(a.y); ng[3] = hi2f(a.y);
;         nv[0] = lo2f(b.x); nv[1] = hi2f(b.x); nv[2] = lo2f(b.y); nv[3] = hi2f(b.y);
;         const long gr = brow + lr;
;         const bool valid = (gr >= seq0) && (gr < seq1) && (lr >= 1 || gr == seq0) && (lr <= 254 || gr == seq1 - 1);
;         if (valid) {
;           const float mp = (gr - 1 >= seq0) ? 1.f : 0.f, mn = (gr + 1 < seq1) ? 1.f : 0.f;
;           float o[4];
;           UFOR(x, 4) {
;             const float g = wg[x][0] * pg[x] * mp + wg[x][1] * cgv[x] + wg[x][2] * ng[x] * mn;
;             const float v = wv[x][0] * pvv[x] * mp + wv[x][1] * cv[x] + wv[x][2] * nv[x] * mn;
;             o[x] = siluf_(g) * v;
;           }
;           uint2 pk; pk.x = pk2(o[0], o[1]); pk.y = pk2(o[2], o[3]);
;           *(uint2*)(e.h2 + (size_t)gr * DFF + gc) = pk;
;         }
;         UFOR(x, 4) { pg[x] = cgv[x]; cgv[x] = ng[x]; pvv[x] = cv[x]; cv[x] = nv[x]; }
;       }
.LBB0_1114:
	s_or_b64 exec, exec, s[42:43]
	v_add_u32_e32 v62, 1, v52
	v_min_i32_e32 v52, 0xfe, v62
	v_lshl_add_u32 v52, v52, 9, v64
	v_lshl_add_u64 v[54:55], v[54:55], 0, 1
	ds_read2_b64 v[58:61], v52 offset0:64 offset1:96
	v_cmp_le_i32_e32 vcc, s50, v54
	v_cmp_gt_i32_e64 s[42:43], s52, v54
	s_and_b64 s[42:43], vcc, s[42:43]
	v_cmp_eq_u32_e32 vcc, s58, v26
	s_or_b64 s[62:63], s[40:41], vcc
	s_and_b64 s[62:63], s[42:43], s[62:63]
	v_cmp_gt_i32_e32 vcc, s27, v62
	v_cmp_eq_u32_e64 s[42:43], s58, v34
	s_or_b64 s[42:43], vcc, s[42:43]
	s_waitcnt lgkmcnt(0)
	v_lshlrev_b32_e32 v52, 16, v58
	v_lshlrev_b32_e32 v53, 16, v59
	v_and_b32_e32 v57, 0xffff0000, v59
	v_and_b32_e32 v56, 0xffff0000, v58
	v_lshlrev_b32_e32 v58, 16, v60
	v_lshlrev_b32_e32 v59, 16, v61
	v_and_b32_e32 v61, 0xffff0000, v61
	v_and_b32_e32 v60, 0xffff0000, v60
	s_and_b64 s[62:63], s[62:63], s[42:43]
	s_and_saveexec_b64 s[42:43], s[62:63]
	s_cbranch_execz .LBB0_1111
	v_cmp_lt_i32_e32 vcc, s50, v54
	v_pk_mul_f32 v[46:47], v[12:13], v[46:47]
	v_pk_mul_f32 v[66:67], v[14:15], v[52:53]
	v_cndmask_b32_e64 v62, 0, 1.0, vcc
	v_cmp_gt_i32_e32 vcc, s56, v54
	v_pk_mul_f32 v[46:47], v[46:47], v[62:63] op_sel_hi:[1,0]
	v_pk_mul_f32 v[44:45], v[22:23], v[44:45]
	v_cndmask_b32_e64 v54, 0, 1.0, vcc
	v_pk_fma_f32 v[46:47], v[0:1], v[36:37], v[46:47]
	v_pk_mul_f32 v[44:45], v[44:45], v[62:63] op_sel_hi:[1,0]
	v_pk_fma_f32 v[46:47], v[66:67], v[54:55], v[46:47] op_sel_hi:[1,0,1]
	v_pk_mul_f32 v[50:51], v[4:5], v[50:51]
	v_pk_mul_f32 v[70:71], v[20:21], v[56:57]
	v_pk_mul_f32 v[92:93], v[46:47], v[90:91] op_sel_hi:[1,0]
	v_pk_fma_f32 v[44:45], v[8:9], v[38:39], v[44:45]
	v_pk_mul_f32 v[50:51], v[50:51], v[62:63] op_sel_hi:[1,0]
	v_pk_fma_f32 v[44:45], v[70:71], v[54:55], v[44:45] op_sel_hi:[1,0,1]
	v_pk_mul_f32 v[68:69], v[6:7], v[58:59]
	v_exp_f32_e32 v66, v92
	v_pk_mul_f32 v[94:95], v[44:45], v[90:91] op_sel_hi:[1,0]
	v_pk_fma_f32 v[50:51], v[24:25], v[40:41], v[50:51]
	v_exp_f32_e32 v70, v94
	v_pk_fma_f32 v[50:51], v[54:55], v[68:69], v[50:51] op_sel_hi:[0,1,1]
	v_exp_f32_e32 v67, v93
	v_pk_mul_f32 v[48:49], v[18:19], v[48:49]
	v_pk_mul_f32 v[72:73], v[2:3], v[60:61]
	v_pk_add_f32 v[66:67], v[66:67], 1.0 op_sel_hi:[1,0]
	v_div_scale_f32 v80, vcc, v66, v66, v46
	v_div_scale_f32 v81, vcc, v67, v67, v47
	v_rcp_f32_e32 v82, v80
	v_rcp_f32_e32 v83, v81
	v_div_scale_f32 v86, s[62:63], v46, v66, v46
	v_div_scale_f32 v87, vcc, v47, v67, v47
	v_pk_fma_f32 v[84:85], v[80:81], v[82:83], 1.0 op_sel_hi:[1,1,0] neg_lo:[1,0,0] neg_hi:[1,0,0]
	v_pk_fma_f32 v[82:83], v[84:85], v[82:83], v[82:83]
	v_pk_mul_f32 v[88:89], v[86:87], v[82:83]
	v_pk_fma_f32 v[84:85], v[80:81], v[88:89], v[86:87] neg_lo:[1,0,0] neg_hi:[1,0,0]
	v_pk_fma_f32 v[88:89], v[84:85], v[82:83], v[88:89]
	v_pk_fma_f32 v[84:85], v[80:81], v[88:89], v[86:87] neg_lo:[1,0,0] neg_hi:[1,0,0]
	v_div_fmas_f32 v85, v85, v83, v89
	s_mov_b64 vcc, s[62:63]
	v_div_fmas_f32 v84, v84, v82, v88
	v_div_fixup_f32 v47, v85, v67, v47
	v_div_fixup_f32 v46, v84, v66, v46
	v_pk_mul_f32 v[46:47], v[50:51], v[46:47]
	v_exp_f32_e32 v71, v95
	v_pk_mul_f32 v[48:49], v[48:49], v[62:63] op_sel_hi:[1,0]
	v_pk_add_f32 v[50:51], v[70:71], 1.0 op_sel_hi:[1,0]
	v_pk_fma_f32 v[48:49], v[16:17], v[42:43], v[48:49]
	v_pk_fma_f32 v[48:49], v[54:55], v[72:73], v[48:49] op_sel_hi:[0,1,1]
	v_div_scale_f32 v80, vcc, v50, v50, v44
	v_div_scale_f32 v81, vcc, v51, v51, v45
	v_rcp_f32_e32 v82, v80
	v_rcp_f32_e32 v83, v81
	v_div_scale_f32 v86, s[62:63], v44, v50, v44
	v_div_scale_f32 v87, vcc, v45, v51, v45
	v_pk_fma_f32 v[84:85], v[80:81], v[82:83], 1.0 op_sel_hi:[1,1,0] neg_lo:[1,0,0] neg_hi:[1,0,0]
	v_pk_fma_f32 v[82:83], v[84:85], v[82:83], v[82:83]
	v_pk_mul_f32 v[88:89], v[86:87], v[82:83]
	v_pk_fma_f32 v[84:85], v[80:81], v[88:89], v[86:87] neg_lo:[1,0,0] neg_hi:[1,0,0]
	v_pk_fma_f32 v[88:89], v[84:85], v[82:83], v[88:89]
	v_pk_fma_f32 v[84:85], v[80:81], v[88:89], v[86:87] neg_lo:[1,0,0] neg_hi:[1,0,0]
	v_div_fmas_f32 v85, v85, v83, v89
	s_mov_b64 vcc, s[62:63]
	v_div_fmas_f32 v84, v84, v82, v88
	v_div_fixup_f32 v45, v85, v51, v45
	v_div_fixup_f32 v44, v84, v50, v44
	v_pk_mul_f32 v[44:45], v[48:49], v[44:45]
	v_cvt_pk_bf16_f32 v45, v47, v45
	v_cvt_pk_bf16_f32 v44, v46, v44
	global_store_dwordx2 v[30:31], v[44:45], off
	s_branch .LBB0_1111
